# attention: fast path for the K0/K1 tile loads when all key rows are in range (no clamps, immediates off a running base)
# baseline (speedup 1.0000x reference)
; #define LAS __attribute__((address_space(3)))
; #define ATT_LOADK(buf, grp) do { _Pragma("unroll") for (int tt = 0; tt < 3; ++tt) { int ki = kbase + 16 * ((grp) * 3 + tt); ki = ki < 0 ? 0 : (ki > a.m - 1 ? a.m - 1 : ki); \
;             const bf16_t* kp = kcol + (size_t)ki * 128; \
;             _Pragma("unroll") for (int ks = 0; ks < 4; ++ks) Kf[buf][tt][ks] = *(const bf16x8*)(kp + 32 * ks); } } while (0)
; __device__ __forceinline__ void attn_phase(LAS unsigned char* lds, bf16_t* qkv, float* lse, const float* biasT, int G) {
;     ...
;         const AttnItem a = attn_item(pair * 2 + half);
; #pragma unroll
;         for (int pass = 0; pass < 12; ++pass) *(LAS u32x4*)(vs + (pass * 16 + (ht >> 4)) * VS_PITCH + (ht & 15) * 16) = vreg[pass];
;         if (ht < 129) bs[16 + ht] = biasT[a.head * 132 + ht];
;         __syncthreads();
;         const size_t tokq = (size_t)(a.pos0 + a.r + ((16 * w4 + li) << a.dsh));
;         const int pbase = a.seq_base + a.r * a.m;
;         bf16_t* qp = qkv + ((size_t)a.head * M_TOK + pbase + a.i0 + 16 * w4 + li) * 128;
;         bf16x8 Qf[4];
; #pragma unroll
;         for (int ks = 0; ks < 4; ++ks) Qf[ks] = *(const bf16x8*)(qp + 32 * ks + 8 * lg);
;         const int kbase = a.i0 - 64 + 16 * w4 + li;
;         const bf16_t* kcol = qkv + ((size_t)(12 + a.head) * M_TOK + pbase) * 128 + 8 * lg;
;         f32x4 sa[10];
;         bf16x8 Kf[2][3][4];
;     ...
;         ATT_LOADK(0, 0); ATT_LOADK(1, 1);
.LBB0_425:
	s_or_b64 exec, exec, s[0:1]
	s_mul_i32 s0, s10, 0xfffffd00
	s_add_i32 s0, s0, s9
	s_lshl_b32 s1, s0, 6
	s_and_b32 s9, s1, 0xffffe000
	s_cmpk_lt_i32 s0, 0x200
	s_cselect_b32 s0, 13, 14
	s_cselect_b32 s9, s9, 0x8000
	s_ashr_i32 s11, s10, 1
	s_and_b32 s12, s11, -2
	s_sub_i32 s11, s0, s12
	s_sub_i32 s30, s1, s9
	s_ashr_i32 s96, s30, s11
	s_lshl_b32 s31, s96, s11
	s_sub_i32 s13, s30, s31
	s_add_i32 s16, s31, s9
	s_mul_hi_i32 s0, s10, 0xc000
	s_ashr_i32 s18, s16, 31
	s_ashr_i32 s1, s13, 31
	s_mul_i32 s17, s10, 0xc000
	v_mov_b32_e32 v3, s0
	s_add_u32 s0, s13, s16
	v_or_b32_e32 v2, s17, v184
	s_addc_u32 s1, s1, s18
	v_lshl_add_u64 v[2:3], s[0:1], 0, v[2:3]
	v_readlane_b32 s0, v250, 21
	s_add_i32 s15, s13, s0
	s_add_i32 s0, s10, 12
	s_add_i32 s17, s17, 0x90000
	v_lshlrev_b64 v[2:3], 8, v[2:3]
	s_mul_hi_i32 s1, s0, 0xc000
	s_add_u32 s0, s17, s16
	v_lshl_add_u64 v[194:195], s[92:93], 0, v[2:3]
	v_mov_b32_e32 v191, v1
	s_addc_u32 s1, s1, s18
	v_lshl_add_u64 v[2:3], v[194:195], 0, v[190:191]
	s_lshl_b64 s[0:1], s[0:1], 8
	global_load_dwordx4 v[96:99], v[2:3], off
	global_load_dwordx4 v[92:95], v[2:3], off offset:64
	global_load_dwordx4 v[88:91], v[2:3], off offset:128
	global_load_dwordx4 v[52:55], v[2:3], off offset:192
	v_add_u32_e32 v0, s15, v216
	v_lshl_add_u64 v[2:3], v[186:187], 0, s[0:1]
	s_bfm_b32 s0, s11, 0
	s_sub_i32 s32, s0, 0x50
	v_cmp_ge_u32_e32 vcc, s32, v0
	s_cmp_eq_u64 vcc, exec
	s_cbranch_scc0 .Lattn_kslow
	v_lshlrev_b32_e32 v254, 8, v0
	v_mov_b32_e32 v255, 0
	v_add_u32_e32 v254, 0x1000, v254
	s_mov_b64 vcc, 0x2000
	v_lshl_add_u64 v[254:255], v[2:3], 0, v[254:255]
	global_load_dwordx4 v[68:71], v[254:255], off offset:-4096
	global_load_dwordx4 v[72:75], v[254:255], off offset:-4032
	global_load_dwordx4 v[80:83], v[254:255], off offset:-3968
	global_load_dwordx4 v[84:87], v[254:255], off offset:-3904
	global_load_dwordx4 v[116:119], v[254:255], off
	global_load_dwordx4 v[136:139], v[254:255], off offset:64
	global_load_dwordx4 v[140:143], v[254:255], off offset:128
	global_load_dwordx4 v[144:147], v[254:255], off offset:192
	v_lshl_add_u64 v[254:255], vcc, 0, v[254:255]
	global_load_dwordx4 v[148:151], v[254:255], off offset:-4096
	global_load_dwordx4 v[152:155], v[254:255], off offset:-4032
	global_load_dwordx4 v[156:159], v[254:255], off offset:-3968
	global_load_dwordx4 v[160:163], v[254:255], off offset:-3904
	global_load_dwordx4 v[56:59], v[254:255], off
	global_load_dwordx4 v[60:63], v[254:255], off offset:64
	global_load_dwordx4 v[64:67], v[254:255], off offset:128
	global_load_dwordx4 v[76:79], v[254:255], off offset:192
	v_lshl_add_u64 v[254:255], vcc, 0, v[254:255]
	global_load_dwordx4 v[100:103], v[254:255], off offset:-4096
	global_load_dwordx4 v[104:107], v[254:255], off offset:-4032
	global_load_dwordx4 v[108:111], v[254:255], off offset:-3968
	global_load_dwordx4 v[112:115], v[254:255], off offset:-3904
	global_load_dwordx4 v[120:123], v[254:255], off
	global_load_dwordx4 v[124:127], v[254:255], off offset:64
	global_load_dwordx4 v[128:131], v[254:255], off offset:128
	global_load_dwordx4 v[132:135], v[254:255], off offset:192
	s_branch .Lattn_kjoin
.Lattn_kslow:
	v_min_i32_e32 v56, s0, v0
	v_ashrrev_i32_e32 v57, 31, v56
	v_lshlrev_b64 v[56:57], 7, v[56:57]
	v_cmp_lt_i32_e32 vcc, -1, v0
	s_movk_i32 s1, 0xffef
	v_add_u32_e32 v58, 48, v0
	v_cndmask_b32_e32 v57, 0, v57, vcc
	v_cndmask_b32_e32 v56, 0, v56, vcc
	v_lshl_add_u64 v[56:57], v[56:57], 1, v[2:3]
	global_load_dwordx4 v[68:71], v[56:57], off
	global_load_dwordx4 v[72:75], v[56:57], off offset:64
	global_load_dwordx4 v[80:83], v[56:57], off offset:128
	global_load_dwordx4 v[84:87], v[56:57], off offset:192
	v_add_u32_e32 v56, 16, v0
	v_min_i32_e32 v56, s0, v56
	v_ashrrev_i32_e32 v57, 31, v56
	v_lshlrev_b64 v[56:57], 7, v[56:57]
	v_cmp_lt_i32_e32 vcc, s1, v0
	s_movk_i32 s1, 0xffdf
	v_add_u32_e32 v102, 64, v0
	v_cndmask_b32_e32 v57, 0, v57, vcc
	v_cndmask_b32_e32 v56, 0, v56, vcc
	v_lshl_add_u64 v[56:57], v[56:57], 1, v[2:3]
	global_load_dwordx4 v[116:119], v[56:57], off
	global_load_dwordx4 v[136:139], v[56:57], off offset:64
	global_load_dwordx4 v[140:143], v[56:57], off offset:128
	global_load_dwordx4 v[144:147], v[56:57], off offset:192
	v_add_u32_e32 v56, 32, v0
	v_min_i32_e32 v56, s0, v56
	v_ashrrev_i32_e32 v57, 31, v56
	v_lshlrev_b64 v[56:57], 7, v[56:57]
	v_cmp_lt_i32_e32 vcc, s1, v0
	v_min_i32_e32 v100, s0, v102
	v_add_u32_e32 v122, 0x50, v0
	v_cndmask_b32_e32 v57, 0, v57, vcc
	v_cndmask_b32_e32 v56, 0, v56, vcc
	v_lshl_add_u64 v[56:57], v[56:57], 1, v[2:3]
	global_load_dwordx4 v[148:151], v[56:57], off
	global_load_dwordx4 v[152:155], v[56:57], off offset:64
	global_load_dwordx4 v[156:159], v[56:57], off offset:128
	global_load_dwordx4 v[160:163], v[56:57], off offset:192
	v_min_i32_e32 v56, s0, v58
	v_ashrrev_i32_e32 v57, 31, v56
	v_lshlrev_b64 v[56:57], 7, v[56:57]
	v_cmp_lt_i32_e32 vcc, -1, v58
	v_ashrrev_i32_e32 v101, 31, v100
	v_min_i32_e32 v120, s0, v122
	v_cndmask_b32_e32 v57, 0, v57, vcc
	v_cndmask_b32_e32 v56, 0, v56, vcc
	v_lshlrev_b64 v[100:101], 7, v[100:101]
	v_cmp_lt_i32_e32 vcc, -1, v102
	v_ashrrev_i32_e32 v121, 31, v120
	v_lshlrev_b64 v[120:121], 7, v[120:121]
	v_cndmask_b32_e32 v101, 0, v101, vcc
	v_cndmask_b32_e32 v100, 0, v100, vcc
	v_cmp_lt_i32_e32 vcc, -1, v122
	v_lshl_add_u64 v[76:77], v[56:57], 1, v[2:3]
	v_lshl_add_u64 v[112:113], v[100:101], 1, v[2:3]
	v_cndmask_b32_e32 v121, 0, v121, vcc
	v_cndmask_b32_e32 v120, 0, v120, vcc
	v_lshl_add_u64 v[132:133], v[120:121], 1, v[2:3]
	global_load_dwordx4 v[56:59], v[76:77], off
	global_load_dwordx4 v[60:63], v[76:77], off offset:64
	global_load_dwordx4 v[64:67], v[76:77], off offset:128
	s_nop 0
	global_load_dwordx4 v[76:79], v[76:77], off offset:192
	s_nop 0
	global_load_dwordx4 v[100:103], v[112:113], off
	global_load_dwordx4 v[104:107], v[112:113], off offset:64
	global_load_dwordx4 v[108:111], v[112:113], off offset:128
	s_nop 0
	global_load_dwordx4 v[112:115], v[112:113], off offset:192
	s_nop 0
	global_load_dwordx4 v[120:123], v[132:133], off
	global_load_dwordx4 v[124:127], v[132:133], off offset:64
	global_load_dwordx4 v[128:131], v[132:133], off offset:128
	s_nop 0
	global_load_dwordx4 v[132:135], v[132:133], off offset:192
; #define ATT_LOADK(buf, grp) do { _Pragma("unroll") for (int tt = 0; tt < 3; ++tt) { int ki = kbase + 16 * ((grp) * 3 + tt); ki = ki < 0 ? 0 : (ki > a.m - 1 ? a.m - 1 : ki); \
;             const bf16_t* kp = kcol + (size_t)ki * 128; \
;             _Pragma("unroll") for (int ks = 0; ks < 4; ++ks) Kf[buf][tt][ks] = *(const bf16x8*)(kp + 32 * ks); } } while (0)
; #define ATT_MMAK(buf, grp) do { _Pragma("unroll") for (int tt = 0; tt < 3; ++tt) { f32x4 acc_ = (f32x4){0.f, 0.f, 0.f, 0.f}; \
;             _Pragma("unroll") for (int ks = 0; ks < 4; ++ks) acc_ = __builtin_amdgcn_mfma_f32_16x16x32_bf16(Kf[buf][tt][ks], Qf[ks], acc_, 0, 0, 0); sa[(grp) * 3 + tt] = acc_; } } while (0)
; __device__ __forceinline__ void attn_load_v(const AttnItem& a, const bf16_t* qkv, int ht, u32x4 (&vreg)[12]) {
; #pragma unroll
;     for (int pass = 0; pass < 12; ++pass) {
;         const int row = pass * 16 + (ht >> 4), ch = ht & 15, ki = a.i0 - 64 + row;
;         u32x4 val = (u32x4){0u, 0u, 0u, 0u};
;         if (ki >= 0 && ki < a.m) val = *(const u32x4*)(qkv + ((size_t)(24 + a.head) * M_TOK + a.seq_base + a.r * a.m + ki) * 128 + ch * 8);
;         vreg[pass] = val;
;     }
; }
; __device__ __forceinline__ void attn_phase(LAS unsigned char* lds, bf16_t* qkv, float* lse, const float* biasT, int G) {
;     ...
;         ATT_LOADK(0, 0); ATT_LOADK(1, 1);
;         __builtin_amdgcn_sched_barrier(0);
;         ATT_MMAK(0, 0);
;         __builtin_amdgcn_sched_barrier(0);
;         ATT_LOADK(0, 2);
;         if (pairn < 4608) { const AttnItem an = attn_item(pairn * 2 + half); attn_load_v(an, qkv, ht, vreg); }
.Lattn_kjoin:
	s_waitcnt vmcnt(23)
	v_mfma_f32_16x16x32_bf16 v[68:71], v[68:71], v[96:99], 0
	s_waitcnt vmcnt(22)
	v_mfma_f32_16x16x32_bf16 v[68:71], v[72:75], v[92:95], v[68:71]
	s_waitcnt vmcnt(21)
	v_mfma_f32_16x16x32_bf16 v[68:71], v[80:83], v[88:91], v[68:71]
	s_waitcnt vmcnt(20)
	v_mfma_f32_16x16x32_bf16 v[84:87], v[84:87], v[52:55], v[68:71]
	s_waitcnt vmcnt(19)
	v_mfma_f32_16x16x32_bf16 v[68:71], v[116:119], v[96:99], 0
	s_waitcnt vmcnt(18)
	v_mfma_f32_16x16x32_bf16 v[68:71], v[136:139], v[92:95], v[68:71]
	s_waitcnt vmcnt(17)
	v_mfma_f32_16x16x32_bf16 v[68:71], v[140:143], v[88:91], v[68:71]
	s_waitcnt vmcnt(16)
	v_mfma_f32_16x16x32_bf16 v[72:75], v[144:147], v[52:55], v[68:71]
	s_waitcnt vmcnt(15)
	v_mfma_f32_16x16x32_bf16 v[68:71], v[148:151], v[96:99], 0
	s_waitcnt vmcnt(14)
	v_mfma_f32_16x16x32_bf16 v[68:71], v[152:155], v[92:95], v[68:71]
	s_waitcnt vmcnt(13)
	v_mfma_f32_16x16x32_bf16 v[68:71], v[156:159], v[88:91], v[68:71]
	s_waitcnt vmcnt(12)
	v_mfma_f32_16x16x32_bf16 v[68:71], v[160:163], v[52:55], v[68:71]
	v_add_u32_e32 v82, 0x60, v0
	v_min_i32_e32 v80, s0, v82
	v_ashrrev_i32_e32 v81, 31, v80
	v_lshlrev_b64 v[80:81], 7, v[80:81]
	v_cmp_lt_i32_e32 vcc, -1, v82
	v_add_u32_e32 v82, 0x70, v0
	v_add_u32_e32 v0, 0x80, v0
	v_cndmask_b32_e32 v81, 0, v81, vcc
	v_cndmask_b32_e32 v80, 0, v80, vcc
	v_lshl_add_u64 v[80:81], v[80:81], 1, v[2:3]
	global_load_dwordx4 v[136:139], v[80:81], off
	global_load_dwordx4 v[140:143], v[80:81], off offset:64
	global_load_dwordx4 v[144:147], v[80:81], off offset:128
	global_load_dwordx4 v[148:151], v[80:81], off offset:192
	v_min_i32_e32 v80, s0, v82
	v_ashrrev_i32_e32 v81, 31, v80
	v_lshlrev_b64 v[80:81], 7, v[80:81]
	v_cmp_lt_i32_e32 vcc, -1, v82
	s_cmpk_gt_i32 s14, 0x11ff
	s_nop 0
	v_cndmask_b32_e32 v81, 0, v81, vcc
	v_cndmask_b32_e32 v80, 0, v80, vcc
	v_lshl_add_u64 v[80:81], v[80:81], 1, v[2:3]
	global_load_dwordx4 v[152:155], v[80:81], off
	global_load_dwordx4 v[156:159], v[80:81], off offset:64
	global_load_dwordx4 v[160:163], v[80:81], off offset:128
	global_load_dwordx4 v[164:167], v[80:81], off offset:192
	v_min_i32_e32 v80, s0, v0
	v_ashrrev_i32_e32 v81, 31, v80
	v_lshlrev_b64 v[80:81], 7, v[80:81]
	v_cmp_lt_i32_e32 vcc, -1, v0
	s_nop 1
	v_cndmask_b32_e32 v81, 0, v81, vcc
	v_cndmask_b32_e32 v80, 0, v80, vcc
	v_lshl_add_u64 v[2:3], v[80:81], 1, v[2:3]
	global_load_dwordx4 v[176:179], v[2:3], off
	global_load_dwordx4 v[172:175], v[2:3], off offset:64
	global_load_dwordx4 v[168:171], v[2:3], off offset:128
	global_load_dwordx4 v[116:119], v[2:3], off offset:192
	s_cbranch_scc1 .LBB0_451
	s_lshl_b32 s0, s14, 1
	s_add_i32 s0, s0, s94
	s_mul_hi_i32 s1, s0, 0x2aaaaaab
	s_lshr_b32 s14, s1, 31
	s_ashr_i32 s1, s1, 7
	s_add_i32 s14, s1, s14
	s_mul_i32 s1, s14, 0xfffffd00
	s_add_i32 s1, s1, s0
	s_lshl_b32 s0, s1, 6
	s_and_b32 s16, s0, 0xffffe000
	s_cmpk_lt_i32 s1, 0x200
	s_cselect_b32 s1, 13, 14
	s_cselect_b32 s16, s16, 0x8000
	s_ashr_i32 s17, s14, 1
	s_and_b32 s17, s17, -2
	s_sub_i32 s1, s1, s17
	s_lshl_b32 s18, 1, s1
	s_sub_i32 s0, s0, s16
	s_lshl_b32 s1, -1, s1
	s_and_b32 s17, s1, s0
	s_sub_i32 s19, s0, s17
	s_cmp_lt_i32 s19, 64
	s_cbranch_scc1 .Lattn_vslow
	s_add_i32 s0, s19, 0x80
	s_cmp_gt_i32 s0, s18
	s_cbranch_scc1 .Lattn_vslow
	s_add_i32 s28, s14, 24
	s_mul_i32 s28, s28, 0xc000
	s_add_i32 s28, s28, s16
	s_add_i32 s28, s28, s17
	s_add_i32 s28, s28, s19
	v_add_u32_e32 v0, s28, v220
	v_lshlrev_b32_e32 v0, 8, v0
	s_mov_b64 s[28:29], 0x1000
	v_lshl_add_u64 v[2:3], v[188:189], 0, v[0:1]
	v_lshl_add_u64 v[2:3], s[28:29], 0, v[2:3]
	s_mov_b64 s[28:29], 0x2000
	global_load_dwordx4 v[8:11], v[2:3], off offset:-4096
	global_load_dwordx4 v[4:7], v[2:3], off
	v_lshl_add_u64 v[2:3], s[28:29], 0, v[2:3]
	global_load_dwordx4 v[12:15], v[2:3], off offset:-4096
	global_load_dwordx4 v[16:19], v[2:3], off
	v_lshl_add_u64 v[2:3], s[28:29], 0, v[2:3]
	global_load_dwordx4 v[20:23], v[2:3], off offset:-4096
	global_load_dwordx4 v[24:27], v[2:3], off
	v_lshl_add_u64 v[2:3], s[28:29], 0, v[2:3]
	global_load_dwordx4 v[28:31], v[2:3], off offset:-4096
	global_load_dwordx4 v[32:35], v[2:3], off
	v_lshl_add_u64 v[2:3], s[28:29], 0, v[2:3]
	global_load_dwordx4 v[36:39], v[2:3], off offset:-4096
	global_load_dwordx4 v[40:43], v[2:3], off
	v_lshl_add_u64 v[2:3], s[28:29], 0, v[2:3]
	global_load_dwordx4 v[44:47], v[2:3], off offset:-4096
	global_load_dwordx4 v[48:51], v[2:3], off
	s_branch .LBB0_451

; template <bool COOP>
; __global__ void __launch_bounds__(512, 2) fwd_kernel(Params p) {
;     ...
;     }
; }
.LBB0_641:
	s_nop 0
	s_nop 0
	s_nop 0
	s_nop 0
	s_nop 0
	s_nop 0
	s_nop 0
	s_nop 0
	s_nop 0
	s_nop 0
	s_nop 0
	s_nop 0
	s_nop 0
	s_nop 0
	s_nop 0
	s_nop 0
	s_nop 0
	s_nop 0
	s_nop 0
	s_nop 0
	s_nop 0
	s_nop 0
	s_nop 0
	s_nop 0
	s_nop 0
	s_nop 0
	s_nop 0
	s_nop 0
	s_nop 0
	s_nop 0
	s_nop 0
	s_nop 0
	s_nop 0
	s_nop 0
	s_nop 0
	s_nop 0
	s_nop 0
	s_nop 0
	s_nop 0
	s_nop 0
	s_nop 0
	s_nop 0
	s_nop 0
	s_nop 0
	s_nop 0
	s_nop 0
	s_nop 0
	s_nop 0
	s_nop 0
	s_nop 0
	s_nop 0
	s_nop 0
	s_nop 0
	s_nop 0
	s_nop 0
	s_nop 0
	s_nop 0
	s_nop 0
	s_nop 0
	s_nop 0
	s_nop 0
	s_nop 0
	s_nop 0
	s_nop 0
	s_nop 0
	s_nop 0
	s_nop 0
	s_nop 0
	s_nop 0
	s_nop 0
	s_nop 0
	s_nop 0
	s_nop 0
	s_nop 0
	s_nop 0
	s_nop 0
	s_nop 0
	s_nop 0
	s_nop 0
	s_nop 0
	s_nop 0
	s_nop 0
	s_nop 0
	s_nop 0
	s_nop 0
	s_nop 0
	s_nop 0
	s_nop 0
	s_nop 0
	s_nop 0
	s_nop 0
	s_nop 0
	s_nop 0
	s_nop 0
	s_nop 0
	s_nop 0
	s_nop 0
	s_nop 0
	s_nop 0
	s_nop 0
	s_nop 0
	s_nop 0
	s_nop 0
	s_nop 0
	s_nop 0
	s_nop 0
	s_nop 0
	s_nop 0
	s_nop 0
	s_nop 0
	s_nop 0
	s_nop 0
	s_nop 0
	s_nop 0
	s_nop 0
	s_nop 0
	s_nop 0
	s_nop 0
	s_nop 0
	s_nop 0
	s_nop 0
	s_nop 0
	s_nop 0
	s_nop 0
	s_nop 0
	s_nop 0
	s_nop 0
	s_nop 0
	s_nop 0
	s_nop 0
	s_nop 0
	s_nop 0
	s_nop 0
	s_nop 0
	s_nop 0
	s_nop 0
	s_nop 0
	s_nop 0
	s_nop 0
	s_nop 0
	s_nop 0
	s_nop 0
	s_nop 0
	s_nop 0
	s_nop 0
	s_nop 0
	s_nop 0
	s_nop 0
	s_nop 0
	s_nop 0
	s_nop 0
	s_nop 0
	s_nop 0
	s_nop 0
	s_nop 0
	s_nop 0
	s_nop 0
	s_nop 0
	s_nop 0
	s_nop 0
	s_nop 0
	s_nop 0
	s_nop 0
	s_nop 0
	s_nop 0
	s_nop 0
	s_nop 0
	s_nop 0
	s_nop 0
	s_nop 0
	s_nop 0
	s_nop 0
	s_nop 0
	s_nop 0
	s_nop 0
	s_nop 0
	s_nop 0
	s_nop 0
	s_nop 0
	s_nop 0
	s_nop 0
	s_nop 0
	s_nop 0
	s_nop 0
	s_nop 0
	s_nop 0
	s_nop 0
	s_nop 0
	s_nop 0
	s_nop 0
	s_nop 0
	s_nop 0
	s_nop 0
	s_nop 0
	s_nop 0
	s_nop 0
	s_nop 0
	s_nop 0
	s_nop 0
	s_nop 0
	s_nop 0
	s_nop 0
	s_nop 0
	s_nop 0
	s_nop 0
	s_nop 0
	s_nop 0
	s_nop 0
	s_nop 0
	s_nop 0
	s_nop 0
	s_nop 0
	s_nop 0
	s_nop 0
	s_nop 0
	s_nop 0
	s_nop 0
	s_nop 0
	s_nop 0
	s_nop 0
	s_nop 0
	s_nop 0
	s_nop 0
	s_nop 0
	s_nop 0
	s_nop 0
	s_nop 0
	s_nop 0
	s_nop 0
	s_nop 0
	s_nop 0
	s_nop 0
	s_nop 0
	s_nop 0
	s_nop 0
	s_nop 0
	s_nop 0
	s_nop 0
	s_nop 0
	s_nop 0
	s_nop 0
	s_nop 0
	s_nop 0
	s_nop 0
	s_nop 0
	s_nop 0
	s_nop 0
	s_nop 0
	s_nop 0
	s_nop 0
	s_nop 0
	s_nop 0
	s_nop 0
	s_nop 0
	s_endpgm
